# weight conversion: each half-item's eight f32 loads split over two consecutive retention tiles (four per tile) so the per-CU load path sees about 110-130 KB on every tile instead of 64 / 176 KB altern
# speedup vs baseline: 1.0017x; 1.0017x over previous
; #define RT_BAR() do { asm volatile("s_waitcnt lgkmcnt(0)" ::: "memory"); __builtin_amdgcn_s_barrier(); asm volatile("" ::: "memory"); } while (0)
; __device__ __forceinline__ void p2_ret(const Frame& F, ArgsP a, int layer) {
;     ...
;         for (int uu = 0; uu < 2; ++uu) {
;             const int qi = uu ? p : 15 - p, ntile = 2 * (qi + 1);
;             const size_t tokq = (size_t)b * SEQ + qi * 128;
;             f32x16 oacc[4];
; #pragma unroll
;             for (int db = 0; db < 4; ++db)
; #pragma unroll
;                 for (int r = 0; r < 16; ++r) oacc[db][r] = 0.f;
;             asm volatile("s_waitcnt vmcnt(0)" ::: "memory"); RT_BAR();
;             for (int kt = 0; kt < ntile; ++kt) {
.LBB0_355:
	s_xor_b64 s[72:73], s[74:75], -1
	s_and_b64 s[2:3], s[74:75], exec
	s_waitcnt vmcnt(0)
	s_cselect_b32 s96, s89, s50
	s_waitcnt lgkmcnt(0)
	s_barrier
	s_mov_b32 s12, 0
	s_nop 0
	v_writelane_b32 v255, s12, 59
	s_lshl_b32 s19, s96, 7
	s_lshl_b32 s11, s96, 8
	v_mov_b32_e32 v34, 0
	s_lshl_b32 s29, s96, 1
	s_add_i32 s97, s81, s19
	s_bitset1_b32 s11, 7
	s_mov_b32 s31, 0
	s_mov_b32 s27, s88
	s_mov_b32 s30, 0
	s_mov_b32 s91, 0
	v_mov_b32_e32 v35, v34
	v_mov_b32_e32 v36, v34
	v_mov_b32_e32 v37, v34
	v_mov_b32_e32 v38, v34
	v_mov_b32_e32 v39, v34
	v_mov_b32_e32 v40, v34
	v_mov_b32_e32 v41, v34
	v_mov_b32_e32 v42, v34
	v_mov_b32_e32 v43, v34
	v_mov_b32_e32 v44, v34
	v_mov_b32_e32 v45, v34
	v_mov_b32_e32 v46, v34
	v_mov_b32_e32 v47, v34
	v_mov_b32_e32 v48, v34
	v_mov_b32_e32 v49, v34
	v_mov_b32_e32 v50, v34
	v_mov_b32_e32 v51, v34
	v_mov_b32_e32 v52, v34
	v_mov_b32_e32 v53, v34
	v_mov_b32_e32 v54, v34
	v_mov_b32_e32 v55, v34
	v_mov_b32_e32 v56, v34
	v_mov_b32_e32 v57, v34
	v_mov_b32_e32 v58, v34
	v_mov_b32_e32 v59, v34
	v_mov_b32_e32 v60, v34
	v_mov_b32_e32 v61, v34
	v_mov_b32_e32 v62, v34
	v_mov_b32_e32 v63, v34
	v_mov_b32_e32 v64, v34
	v_mov_b32_e32 v65, v34
	v_mov_b32_e32 v66, v34
	v_mov_b32_e32 v67, v34
	v_mov_b32_e32 v68, v34
	v_mov_b32_e32 v69, v34
	v_mov_b32_e32 v70, v34
	v_mov_b32_e32 v71, v34
	v_mov_b32_e32 v72, v34
	v_mov_b32_e32 v73, v34
	v_mov_b32_e32 v74, v34
	v_mov_b32_e32 v75, v34
	v_mov_b32_e32 v76, v34
	v_mov_b32_e32 v77, v34
	v_mov_b32_e32 v78, v34
	v_mov_b32_e32 v79, v34
	v_mov_b32_e32 v80, v34
	v_mov_b32_e32 v81, v34
	v_mov_b32_e32 v82, v34
	v_mov_b32_e32 v83, v34
	v_mov_b32_e32 v84, v34
	v_mov_b32_e32 v85, v34
	v_mov_b32_e32 v86, v34
	v_mov_b32_e32 v87, v34
	v_mov_b32_e32 v88, v34
	v_mov_b32_e32 v89, v34
	v_mov_b32_e32 v90, v34
	v_mov_b32_e32 v91, v34
	v_mov_b32_e32 v92, v34
	v_mov_b32_e32 v93, v34
	v_mov_b32_e32 v94, v34
	v_mov_b32_e32 v95, v34
	v_mov_b32_e32 v96, v34
	v_mov_b32_e32 v97, v34
	s_branch .LBB0_358

; __device__ __forceinline__ void p2_ret(const Frame& F, ArgsP a, int layer) {
;     ...
;                 const bool cv = cvhi < CV_HALF_ITEMS && ((cvtile++ & 1) == 0); f32x4 cvv[8], cvsc[2];
;                 if (cv) { const CvU cu = cv_decode(a, F.ws, cvhi, layer); cv_load(cu, lane, cvv, cvsc); }
.LBB0_358:
	s_cmp_lt_i32 s36, s93
	s_cselect_b64 s[2:3], -1, 0
	s_mov_b64 s[38:39], -1
	s_cbranch_scc0 .LBB0_383
	s_bitcmp0_b32 s37, 0
	s_cbranch_scc1 .Lch_dec
	v_readlane_b32 s12, v255, 59
	s_cmp_eq_u32 s12, 1
	s_cbranch_scc0 .LBB0_383

; __device__ __forceinline__ void cv_load(const CvU& u, int lane, f32x4 (&v)[8], f32x4 (&sc)[2]) {
;     const int nq = lane & 15, kq = lane >> 4;
;     const float* wp = u.W + (size_t)(u.k0 + 8 * kq) * u.N + u.n0 + 4 * nq;
; #pragma unroll
;     for (int i = 0; i < 8; ++i) v[i] = __builtin_nontemporal_load((const f32x4*)(wp + (size_t)i * u.N));
;     if (u.ks) { sc[0] = *(const f32x4*)(u.ks + 8 * kq); sc[1] = *(const f32x4*)(u.ks + 8 * kq + 4); }
;     else { sc[0] = (f32x4){1.f, 1.f, 1.f, 1.f}; sc[1] = sc[0]; }
; }
.LBB0_380:
	s_bitcmp0_b32 s37, 0
	s_cbranch_scc0 .Lch_B
	v_or_b32_e32 v0, s6, v206
	s_ashr_i32 s5, s6, 31
	v_mul_lo_u32 v4, s77, v0
	s_mul_i32 s5, s76, s5
	v_mad_u64_u32 v[2:3], s[6:7], s76, v0, 0
	s_lshl_b32 s4, s14, 6
	v_add3_u32 v3, v3, s5, v4
	v_lshl_add_u64 v[2:3], v[2:3], 2, s[46:47]
	s_ashr_i32 s5, s4, 31
	v_lshl_add_u64 v[2:3], s[4:5], 2, v[2:3]
	v_lshlrev_b32_e32 v0, 2, v208
	v_lshl_add_u64 v[2:3], v[2:3], 0, v[0:1]
	s_lshl_b64 s[4:5], s[76:77], 2
	v_lshl_add_u64 v[10:11], v[2:3], 0, s[4:5]
	global_load_dwordx4 v[2:5], v[2:3], off nt
	s_nop 0
	global_load_dwordx4 v[6:9], v[10:11], off nt
	v_lshl_add_u64 v[10:11], v[10:11], 0, s[4:5]
	v_lshl_add_u64 v[18:19], v[10:11], 0, s[4:5]
	global_load_dwordx4 v[10:13], v[10:11], off nt
	s_nop 0
	global_load_dwordx4 v[14:17], v[18:19], off nt
	s_add_i32 s12, s30, 0x80
	s_cmp_eq_u32 s12, s11
	s_cbranch_scc1 .Lch_full
	s_mov_b32 s12, 1
	s_nop 0
	v_writelane_b32 v255, s12, 59
	s_branch .Lch_scal
.Lch_full:
	v_lshl_add_u64 v[18:19], v[18:19], 0, s[4:5]
	v_lshl_add_u64 v[26:27], v[18:19], 0, s[4:5]
	global_load_dwordx4 v[18:21], v[18:19], off nt
	s_nop 0
	global_load_dwordx4 v[22:25], v[26:27], off nt
	v_lshl_add_u64 v[26:27], v[26:27], 0, s[4:5]
	v_lshl_add_u64 v[30:31], v[26:27], 0, s[4:5]
	global_load_dwordx4 v[26:29], v[26:27], off nt
	s_nop 0
	global_load_dwordx4 v[30:33], v[30:31], off nt
	s_mov_b32 s12, 2
	s_nop 0
	v_writelane_b32 v255, s12, 59

; __device__ __forceinline__ void cv_load(const CvU& u, int lane, f32x4 (&v)[8], f32x4 (&sc)[2]) {
;     const int nq = lane & 15, kq = lane >> 4;
;     const float* wp = u.W + (size_t)(u.k0 + 8 * kq) * u.N + u.n0 + 4 * nq;
; #pragma unroll
;     for (int i = 0; i < 8; ++i) v[i] = __builtin_nontemporal_load((const f32x4*)(wp + (size_t)i * u.N));
.Lch_B:
	v_or_b32_e32 v0, s6, v206
	s_ashr_i32 s5, s6, 31
	v_mul_lo_u32 v20, s77, v0
	s_mul_i32 s5, s76, s5
	v_mad_u64_u32 v[18:19], s[6:7], s76, v0, 0
	s_lshl_b32 s4, s14, 6
	v_add3_u32 v19, v19, s5, v20
	v_lshl_add_u64 v[18:19], v[18:19], 2, s[46:47]
	s_ashr_i32 s5, s4, 31
	v_lshl_add_u64 v[18:19], s[4:5], 2, v[18:19]
	v_lshlrev_b32_e32 v0, 2, v208
	v_lshl_add_u64 v[18:19], v[18:19], 0, v[0:1]
	s_lshl_b64 s[4:5], s[76:77], 2
	v_lshl_add_u64 v[18:19], s[4:5], 2, v[18:19]
	v_lshl_add_u64 v[26:27], v[18:19], 0, s[4:5]
	global_load_dwordx4 v[18:21], v[18:19], off nt
	s_nop 0
	global_load_dwordx4 v[22:25], v[26:27], off nt
	v_lshl_add_u64 v[26:27], v[26:27], 0, s[4:5]
	v_lshl_add_u64 v[30:31], v[26:27], 0, s[4:5]
	global_load_dwordx4 v[26:29], v[26:27], off nt
	s_nop 0
	global_load_dwordx4 v[30:33], v[30:31], off nt
	s_mov_b32 s12, 2
	s_nop 0
	v_writelane_b32 v255, s12, 59
	s_branch .LBB0_383

; __device__ __forceinline__ CvU cv_decode(ArgsP a, unsigned char* ws, int hi, int layer) {
;     CvU u; int fi = hi >> 1; const int half = hi & 1; int l = layer, kind;
;     if (fi < CV_GLU) kind = 0; else if ((fi -= CV_GLU) < CV_OUT) kind = 1; else { fi -= CV_OUT; kind = 2; l = layer + 1; }
;     int kb, nb;
;     if (kind == 0) { u.W = a->in[I_WGLU] + (size_t)l * DS * DS; u.WT = (bf16_t*)(ws + WS_WTGLU + (size_t)l * DS * DS); u.K = DS; u.N = DS; kb = fi / (DS / 64); nb = fi % (DS / 64); }
;     else if (kind == 1) { u.W = a->in[I_WOUT] + (size_t)l * DM * DM; u.WT = (bf16_t*)(ws + WS_WTOUT) + (size_t)l * DM * DM; u.K = DM; u.N = DM; kb = fi / (DM / 64); nb = fi % (DM / 64); }
;     else { u.W = a->in[I_WIN] + (size_t)l * DM * NPROJ; u.WT = (bf16_t*)(ws + WS_WTIN) + (size_t)l * NPROJ * DM; u.K = DM; u.N = NPROJ; kb = fi / (NPROJ / 64); nb = fi % (NPROJ / 64); }
;     u.k0 = 64 * kb + 32 * half; u.n0 = 64 * nb; u.n0d = u.n0; u.rowperm = 0;
; __device__ __forceinline__ void p2_ret(const Frame& F, ArgsP a, int layer) {
;     ...
;                 if (cv) { const CvU cu = cv_decode(a, F.ws, cvhi, layer); cv_store(cu, lane, cvv, cvsc); cvhi += cvs; }
.Lrk_wd:
	v_readlane_b32 s12, v255, 59
	s_cmp_eq_u32 s12, 2
	s_cbranch_scc0 .LBB0_357
	s_mov_b32 s12, 0
	s_nop 0
	v_writelane_b32 v255, s12, 59
	v_mov_b32_e32 v0, v207
	s_ashr_i32 s14, s36, 1
	s_cmpk_lt_i32 s14, 0x400
	s_cselect_b64 s[4:5], -1, 0
	s_mov_b64 s[70:71], 0
	s_and_b64 vcc, exec, s[4:5]
	s_cbranch_vccnz .LBB0_394
	s_mov_b64 s[46:47], -1
	s_cmpk_gt_u32 s14, 0x13ff
	s_mov_b64 s[6:7], -1
	s_cbranch_scc0 .LBB0_391
	s_add_i32 s12, s14, 0xffffec00
	s_mov_b64 s[6:7], 0
